# same as previous + s_waitcnt lgkmcnt(0) in front of the GDN scan end-of-chunk barrier (LDS image copy complete before other waves read it)
# baseline (speedup 1.0000x reference)
.LBB0_708:
	s_waitcnt lgkmcnt(15)
	v_add_f32_e32 v182, 0, v174
	v_add_f32_e32 v183, v182, v175
	s_mov_b32 s8, 0xd000000
	s_add_u32 s17, s17, 4
	s_waitcnt lgkmcnt(14)
	v_add_f32_e32 v182, v183, v176
	v_add_f32_e32 v183, v182, v177
	s_addc_u32 s18, s18, 0
	s_add_i32 s0, s0, -1
	s_waitcnt lgkmcnt(13)
	v_add_f32_e32 v182, v183, v178
	v_add_f32_e32 v183, v182, v179
	v_lshl_add_u64 v[122:123], v[122:123], 0, s[6:7]
	s_waitcnt lgkmcnt(12)
	v_add_f32_e32 v182, v183, v180
	v_add_f32_e32 v182, v182, v181
	v_fmamk_f32 v182, v182, 0x3c000000, v162
	v_rsq_f32_e32 v88, v182
	v_lshl_add_u64 v[126:127], v[126:127], 0, s[6:7]
	s_cmp_lg_u32 s0, 0
	s_waitcnt lgkmcnt(10)
	v_lshlrev_b32_e32 v90, 16, v84
	v_and_b32_e32 v91, 0xffff0000, v84
	v_pk_mul_f32 v[90:91], v[88:89], v[90:91] op_sel_hi:[0,1]
	v_pk_mul_f32 v[90:91], v[96:97], v[90:91]
	v_cvt_pk_bf16_f32 v84, v90, v91
	v_lshlrev_b32_e32 v92, 16, v85
	v_and_b32_e32 v93, 0xffff0000, v85
	v_pk_mul_f32 v[92:93], v[88:89], v[92:93] op_sel_hi:[0,1]
	v_pk_mul_f32 v[92:93], v[98:99], v[92:93]
	v_cvt_pk_bf16_f32 v85, v92, v93
	v_lshlrev_b32_e32 v94, 16, v86
	v_and_b32_e32 v95, 0xffff0000, v86
	v_pk_mul_f32 v[94:95], v[88:89], v[94:95] op_sel_hi:[0,1]
	v_pk_mul_f32 v[94:95], v[100:101], v[94:95]
	v_cvt_pk_bf16_f32 v86, v94, v95
	v_lshlrev_b32_e32 v90, 16, v87
	v_and_b32_e32 v91, 0xffff0000, v87
	v_pk_mul_f32 v[90:91], v[88:89], v[90:91] op_sel_hi:[0,1]
	v_pk_mul_f32 v[90:91], v[108:109], v[90:91]
	v_cvt_pk_bf16_f32 v87, v90, v91
	v_lshl_add_u64 v[182:183], s[92:93], 0, v[120:121]
	v_add_co_u32_e32 v182, vcc, s8, v182
	s_mov_b64 s[8:9], 0x20000
	v_lshl_add_u64 v[120:121], v[120:121], 0, s[8:9]
	s_mov_b64 s[8:9], 0x4000
	v_addc_co_u32_e32 v183, vcc, 0, v183, vcc
	v_lshl_add_u64 v[124:125], v[124:125], 0, s[8:9]
	v_lshlrev_b32_e32 v92, 16, v80
	v_and_b32_e32 v93, 0xffff0000, v80
	v_pk_mul_f32 v[92:93], v[88:89], v[92:93] op_sel_hi:[0,1]
	v_pk_mul_f32 v[92:93], v[110:111], v[92:93]
	v_cvt_pk_bf16_f32 v80, v92, v93
	v_lshlrev_b32_e32 v94, 16, v81
	v_and_b32_e32 v95, 0xffff0000, v81
	v_pk_mul_f32 v[94:95], v[88:89], v[94:95] op_sel_hi:[0,1]
	v_pk_mul_f32 v[94:95], v[112:113], v[94:95]
	v_cvt_pk_bf16_f32 v81, v94, v95
	v_lshlrev_b32_e32 v90, 16, v82
	v_and_b32_e32 v91, 0xffff0000, v82
	v_pk_mul_f32 v[90:91], v[88:89], v[90:91] op_sel_hi:[0,1]
	v_pk_mul_f32 v[90:91], v[114:115], v[90:91]
	v_cvt_pk_bf16_f32 v82, v90, v91
	v_lshlrev_b32_e32 v92, 16, v83
	v_and_b32_e32 v93, 0xffff0000, v83
	v_pk_mul_f32 v[92:93], v[88:89], v[92:93] op_sel_hi:[0,1]
	v_pk_mul_f32 v[92:93], v[116:117], v[92:93]
	v_cvt_pk_bf16_f32 v83, v92, v93
	global_store_dwordx4 v[182:183], v[84:87], off offset:1024
	global_store_dwordx4 v[182:183], v[80:83], off offset:1040
	s_waitcnt lgkmcnt(0)
	s_barrier
	s_cbranch_scc0 .LBB0_706
